# mixers work queue: the four long pool-sample items handed out first after attention (no longer on the phase tail)
# speedup vs baseline: 1.0008x; 1.0008x over previous
.LBB0_544:
	s_or_b64 exec, exec, s[10:11]
	s_waitcnt vmcnt(7)
	v_mov_b32_e32 v0, s53
	s_waitcnt lgkmcnt(0)
	s_barrier
	ds_read_b32 v0, v0
	s_waitcnt lgkmcnt(0)
	s_barrier
	v_readfirstlane_b32 s81, v0
	s_cmpk_gt_i32 s81, 0x405
	s_cbranch_scc1 .LBB0_779
	s_cmpk_lt_i32 s81, 0x104
	s_cselect_b32 s4, 0x182, -4
	s_cmpk_lt_i32 s81, 0x286
	s_cselect_b32 s4, s4, 0
	s_add_i32 s81, s81, s4
